# 400 more FFN2 gate/up conversion tiles moved from the retention workgroups' P7 tail to P9's idle workgroups (tc4 1208 tiles, P7 tail 200 tiles)
# speedup vs baseline: 1.0054x; 1.0054x over previous
; __device__ __forceinline__ int fresh_tid(int wv) { int l; asm volatile("v_mbcnt_lo_u32_b32 %0, -1, 0\n\tv_mbcnt_hi_u32_b32 %0, -1, %0" : "=v"(l)); return wv * 64 + l; }
; #define LAS __attribute__((address_space(3)))
; __device__ __forceinline__ void tconv_list(const float* wg, const float* wu, const float* wd, const float* win, const float* wout, unsigned char* ws, const int ntiles, LAS float* t, const int wv) {
;     const int tid = fresh_tid(wv); const int G = gridDim.x;
;     float cur[8], nxt[8];
;     int i = blockIdx.x;
;     if (i < ntiles) { const TDesc d = tconv_desc(wg, wu, wd, win, wout, ws, i);
; #pragma unroll
;         for (int e = 0; e < 8; ++e) { const int idx = e * 512 + tid, r = idx >> 6, c = idx & 63; cur[e] = __builtin_nontemporal_load(d.W + (size_t)(d.k0 + r) * d.N + d.n0 + c); } }
.LBB0_689:
	s_cmp_lt_u32 s2, 128
	s_cbranch_scc1 .Ltc2_skip
	v_writelane_b32 v40, s4, 4
	v_writelane_b32 v40, s5, 5
	v_writelane_b32 v40, s6, 6
	v_writelane_b32 v40, s7, 7
	v_writelane_b32 v40, s8, 8
	v_writelane_b32 v40, s9, 9
	v_writelane_b32 v40, s10, 10
	v_writelane_b32 v40, s11, 11
	v_writelane_b32 v40, s12, 12
	v_writelane_b32 v40, s13, 13
	v_writelane_b32 v40, s14, 14
	v_writelane_b32 v40, s15, 15
	v_writelane_b32 v40, s16, 16
	v_writelane_b32 v40, s17, 17
	v_writelane_b32 v40, s18, 18
	v_writelane_b32 v40, s19, 19
	v_writelane_b32 v40, s20, 20
	v_writelane_b32 v40, s21, 21
	v_writelane_b32 v40, s22, 22
	v_writelane_b32 v40, s23, 23
	v_writelane_b32 v40, s24, 24
	v_writelane_b32 v40, s25, 25
	v_writelane_b32 v40, s26, 26
	v_writelane_b32 v40, s27, 27
	v_writelane_b32 v40, s28, 28
	v_writelane_b32 v40, s29, 29
	v_writelane_b32 v40, s30, 30
	v_writelane_b32 v40, s31, 31
	s_load_dwordx2 s[24:25], s[38:39], 0xd8
	s_load_dwordx2 s[26:27], s[38:39], 0xd0
	s_load_dwordx2 s[18:19], s[38:39], 0xb8
	s_load_dwordx2 s[20:21], s[38:39], 0xc0
	s_load_dwordx2 s[22:23], s[38:39], 0xc8
	v_mbcnt_lo_u32_b32 v0, -1, 0
	v_mbcnt_hi_u32_b32 v0, -1, v0
	s_lshr_b32 s28, s33, 6
	v_lshlrev_b32_e32 v1, 2, v0
	v_lshrrev_b32_e32 v2, 5, v0
	v_and_b32_e32 v3, 31, v0
	s_mul_i32 s7, s28, 260
	v_add_u32_e32 v5, s7, v1
	v_mul_u32_u24_e32 v6, 0x208, v3
	s_lshl_b32 s7, s28, 3
	v_lshl_add_u32 v6, v2, 2, v6
	v_add_u32_e32 v6, s7, v6
	v_lshlrev_b32_e32 v3, 2, v3
	s_sub_u32 s4, s2, 128
	s_add_u32 s4, s4, 1208
	s_waitcnt lgkmcnt(0)
	s_cmp_lt_u32 s4, 704
	s_cbranch_scc0 .Ltc2_seg1_0
	s_mov_b32 s7, s4
	s_and_b32 s8, s7, 15
	s_lshr_b32 s9, s7, 4
	s_mul_i32 s7, s8, 720896
	s_lshl_b32 s29, s9, 8
	s_add_u32 s7, s7, s29
	s_mul_i32 s29, s28, 11264
	s_add_u32 s7, s7, s29
	s_add_u32 s10, s18, s7
	s_addc_u32 s11, s19, 0
	s_lshr_b32 s7, s9, 1
	s_lshl_b32 s7, s7, 8
	s_and_b32 s29, s9, 1
	s_lshl_b32 s29, s29, 6
	s_add_u32 s7, s7, s29
	s_mul_i32 s7, s7, 2048
	s_lshl_b32 s29, s8, 7
	s_add_u32 s7, s7, s29
	s_mul_i32 s29, s28, 4096
	s_add_u32 s7, s7, s29
	s_add_u32 s12, s26, 0x2100000
	s_addc_u32 s13, s27, 0
	s_add_u32 s12, s12, s7
	s_addc_u32 s13, s13, 0
	s_mov_b32 s14, 90112
	s_mov_b32 s15, 32768
	s_movk_i32 s16, 2048
	s_branch .Ltc2_segend_0

; __device__ __forceinline__ void tconv_list(const float* wg, const float* wu, const float* wd, const float* win, const float* wout, unsigned char* ws, const int ntiles, LAS float* t, const int wv) {
;     ...
;     for (; i < ntiles; i += G) {
;         const TDesc d = tconv_desc(wg, wu, wd, win, wout, ws, i);
;         { const TDesc dn = tconv_desc(wg, wu, wd, win, wout, ws, i + G < ntiles ? i + G : i);
; #pragma unroll
;             for (int e = 0; e < 8; ++e) { const int idx = e * 512 + tid, r = idx >> 6, c = idx & 63; nxt[e] = __builtin_nontemporal_load(dn.W + (size_t)(dn.k0 + r) * dn.N + dn.n0 + c); } }
.Ltc4_loop:
	s_add_u32 s4, s4, 224
	s_cmp_lt_u32 s4, 1208
	s_cselect_b32 s31, 1, 0
	s_cbranch_scc0 .Ltc4_nonexta
	v_writelane_b32 v40, s8, 32
	v_writelane_b32 v40, s9, 33
	s_cmp_lt_u32 s4, 704
	s_cbranch_scc0 .Ltc4_seg1_1
	s_mov_b32 s7, s4
	s_and_b32 s8, s7, 15
	s_lshr_b32 s9, s7, 4
	s_mul_i32 s7, s8, 720896
	s_lshl_b32 s29, s9, 8
	s_add_u32 s7, s7, s29
	s_mul_i32 s29, s28, 11264
	s_add_u32 s7, s7, s29
	s_add_u32 s10, s18, s7
	s_addc_u32 s11, s19, 0
	s_lshr_b32 s7, s9, 1
	s_lshl_b32 s7, s7, 8
	s_and_b32 s29, s9, 1
	s_lshl_b32 s29, s29, 6
	s_add_u32 s7, s7, s29
	s_mul_i32 s7, s7, 2048
	s_lshl_b32 s29, s8, 7
	s_add_u32 s7, s7, s29
	s_mul_i32 s29, s28, 4096
	s_add_u32 s7, s7, s29
	s_add_u32 s12, s26, 0x2100000
	s_addc_u32 s13, s27, 0
	s_add_u32 s12, s12, s7
	s_addc_u32 s13, s13, 0
	s_mov_b32 s14, 90112
	s_mov_b32 s15, 32768
	s_movk_i32 s16, 2048
	s_branch .Ltc4_segend_1

; __device__ __forceinline__ unsigned cvt_pk_bf16(float lo, float hi) { const f32x2_t v = {lo, hi}; const bf16x2_t b = __builtin_convertvector(v, bf16x2_t); return __builtin_bit_cast(unsigned, b); }
; __device__ __forceinline__ void tconv_list(const float* wg, const float* wu, const float* wd, const float* win, const float* wout, unsigned char* ws, const int ntiles, LAS float* t, const int wv) {
;     ...
; #pragma unroll
;         for (int e = 0; e < 8; ++e) { const int idx = e * 512 + tid, r = idx >> 6, c = idx & 63; t[r * 65 + c] = cur[e]; }
;         __syncthreads();
; #pragma unroll
;         for (int e = 0; e < 4; ++e) { const int idx = e * 512 + tid, n = idx >> 5, kp = idx & 31;
;             const unsigned w = pg8::cvt_pk_bf16(t[(2 * kp) * 65 + n], t[(2 * kp + 1) * 65 + n]);
;             *(unsigned*)(d.Bt + (size_t)(d.brow0 + n) * d.K + d.k0 + 2 * kp) = w; }
;         __syncthreads();
; #pragma unroll
;         for (int e = 0; e < 8; ++e) cur[e] = nxt[e];
;     }
.Ltc4_havea:
	ds_write_b32 v5, v8 offset:0
	ds_write_b32 v5, v9 offset:2080
	ds_write_b32 v5, v10 offset:4160
	ds_write_b32 v5, v11 offset:6240
	ds_write_b32 v5, v12 offset:8320
	ds_write_b32 v5, v13 offset:10400
	ds_write_b32 v5, v14 offset:12480
	ds_write_b32 v5, v15 offset:14560
	v_mad_u32_u24 v4, v2, s30, v3
	s_waitcnt lgkmcnt(0)
	s_barrier
	ds_read2_b32 v[24:25], v6 offset0:0 offset1:65
	ds_read2_b32 v[26:27], v6 offset0:16 offset1:81
	ds_read2_b32 v[28:29], v6 offset0:32 offset1:97
	ds_read2_b32 v[30:31], v6 offset0:48 offset1:113
	s_waitcnt lgkmcnt(3)
	v_cvt_pk_bf16_f32 v32, v24, v25
	s_waitcnt lgkmcnt(2)
	v_cvt_pk_bf16_f32 v33, v26, v27
	s_waitcnt lgkmcnt(1)
	v_cvt_pk_bf16_f32 v34, v28, v29
	s_waitcnt lgkmcnt(0)
	v_cvt_pk_bf16_f32 v35, v30, v31
	global_store_dword v4, v32, s[8:9]
	s_add_u32 s8, s8, s17
	s_addc_u32 s9, s9, 0
	global_store_dword v4, v33, s[8:9]
	s_add_u32 s8, s8, s17
	s_addc_u32 s9, s9, 0
	global_store_dword v4, v34, s[8:9]
	s_add_u32 s8, s8, s17
	s_addc_u32 s9, s9, 0
	global_store_dword v4, v35, s[8:9]
	s_barrier
	s_cmp_eq_u32 s31, 0
	s_cbranch_scc1 .Ltc4_done
	s_mov_b32 s17, s15
	s_mov_b32 s30, s16
	s_mov_b64 s[8:9], s[12:13]
	s_add_u32 s4, s4, 224
	s_cmp_lt_u32 s4, 1208
	s_cselect_b32 s31, 1, 0
	s_cbranch_scc0 .Ltc4_nonextb
	v_writelane_b32 v40, s8, 32
	v_writelane_b32 v40, s9, 33
	s_cmp_lt_u32 s4, 704
	s_cbranch_scc0 .Ltc4_seg1_2
	s_mov_b32 s7, s4
	s_and_b32 s8, s7, 15
	s_lshr_b32 s9, s7, 4
	s_mul_i32 s7, s8, 720896
	s_lshl_b32 s29, s9, 8
	s_add_u32 s7, s7, s29
	s_mul_i32 s29, s28, 11264
	s_add_u32 s7, s7, s29
	s_add_u32 s10, s18, s7
	s_addc_u32 s11, s19, 0
	s_lshr_b32 s7, s9, 1
	s_lshl_b32 s7, s7, 8
	s_and_b32 s29, s9, 1
	s_lshl_b32 s29, s29, 6
	s_add_u32 s7, s7, s29
	s_mul_i32 s7, s7, 2048
	s_lshl_b32 s29, s8, 7
	s_add_u32 s7, s7, s29
	s_mul_i32 s29, s28, 4096
	s_add_u32 s7, s7, s29
	s_add_u32 s12, s26, 0x2100000
	s_addc_u32 s13, s27, 0
	s_add_u32 s12, s12, s7
	s_addc_u32 s13, s13, 0
	s_mov_b32 s14, 90112
	s_mov_b32 s15, 32768
	s_movk_i32 s16, 2048
	s_branch .Ltc4_segend_2
